# v84 + instruction selection in the attention softmax: packed v_pk_add_f32 row sums split into scalar v_add_f32 pairs (same bytes, same placement)
# speedup vs baseline: 1.0136x; 1.0039x over previous
.LBB0_349:
	v_exp_f32_e32 v198, v112
	v_exp_f32_e32 v199, v80
	v_exp_f32_e32 v202, v113
	v_exp_f32_e32 v203, v81
	v_exp_f32_e32 v204, v114
	v_exp_f32_e32 v205, v82
	v_exp_f32_e32 v206, v115
	v_exp_f32_e32 v207, v83
	v_exp_f32_e32 v208, v116
	v_exp_f32_e32 v209, v84
	v_exp_f32_e32 v211, v85
	v_add_f32_e32 v84, 0, v198
	v_add_f32_e32 v85, 0, v199
	v_exp_f32_e32 v210, v117
	v_add_f32_e32 v84, v202, v84
	v_add_f32_e32 v85, v203, v85
	v_exp_f32_e32 v212, v118
	v_exp_f32_e32 v213, v86
	v_add_f32_e32 v84, v204, v84
	v_add_f32_e32 v85, v205, v85
	v_exp_f32_e32 v214, v119
	v_exp_f32_e32 v215, v87
	v_add_f32_e32 v84, v206, v84
	v_add_f32_e32 v85, v207, v85
	v_exp_f32_e32 v120, v120
	v_exp_f32_e32 v216, v121
	v_exp_f32_e32 v121, v88
	v_add_f32_e32 v84, v208, v84
	v_add_f32_e32 v85, v209, v85
	v_exp_f32_e32 v217, v89
	v_add_f32_e32 v84, v210, v84
	v_add_f32_e32 v85, v211, v85
	v_exp_f32_e32 v122, v122
	v_exp_f32_e32 v218, v123
	v_exp_f32_e32 v123, v90
	v_add_f32_e32 v84, v212, v84
	v_add_f32_e32 v85, v213, v85
	v_exp_f32_e32 v219, v91
	v_add_f32_e32 v84, v214, v84
	v_add_f32_e32 v85, v215, v85
	v_exp_f32_e32 v124, v124
	v_exp_f32_e32 v220, v125
	v_add_f32_e32 v84, v120, v84
	v_add_f32_e32 v85, v121, v85
	v_exp_f32_e32 v125, v92
	v_add_f32_e32 v84, v216, v84
	v_add_f32_e32 v85, v217, v85
	v_exp_f32_e32 v221, v93
	v_exp_f32_e32 v126, v126
	v_exp_f32_e32 v222, v127
	v_add_f32_e32 v88, v122, v84
	v_add_f32_e32 v89, v123, v85
	v_exp_f32_e32 v127, v94
	v_exp_f32_e32 v223, v95
	v_exp_f32_e32 v225, v64
	v_exp_f32_e32 v227, v65
	v_add_f32_e32 v64, v218, v88
	v_add_f32_e32 v65, v219, v89
	v_exp_f32_e32 v224, v96
	v_add_f32_e32 v64, v124, v64
	v_add_f32_e32 v65, v125, v65
	v_exp_f32_e32 v226, v97
	v_add_f32_e32 v64, v220, v64
	v_add_f32_e32 v65, v221, v65
	v_exp_f32_e32 v228, v98
	v_exp_f32_e32 v229, v66
	v_add_f32_e32 v64, v126, v64
	v_add_f32_e32 v65, v127, v65
	v_exp_f32_e32 v230, v99
	v_exp_f32_e32 v231, v67
	v_add_f32_e32 v64, v222, v64
	v_add_f32_e32 v65, v223, v65
	v_exp_f32_e32 v232, v100
	v_exp_f32_e32 v233, v68
	v_add_f32_e32 v64, v224, v64
	v_add_f32_e32 v65, v225, v65
	v_exp_f32_e32 v234, v101
	v_exp_f32_e32 v235, v69
	v_add_f32_e32 v64, v226, v64
	v_add_f32_e32 v65, v227, v65
	v_exp_f32_e32 v236, v102
	v_add_f32_e32 v64, v228, v64
	v_add_f32_e32 v65, v229, v65
	v_exp_f32_e32 v237, v70
	v_exp_f32_e32 v238, v103
	v_add_f32_e32 v64, v230, v64
	v_add_f32_e32 v65, v231, v65
	v_exp_f32_e32 v239, v71
	v_exp_f32_e32 v104, v104
	v_exp_f32_e32 v240, v105
	v_add_f32_e32 v64, v232, v64
	v_add_f32_e32 v65, v233, v65
	v_exp_f32_e32 v105, v72
	v_add_f32_e32 v68, v234, v64
	v_add_f32_e32 v69, v235, v65
	v_exp_f32_e32 v241, v73
	v_exp_f32_e32 v106, v106
	v_exp_f32_e32 v242, v107
	v_exp_f32_e32 v107, v74
	v_add_f32_e32 v68, v236, v68
	v_add_f32_e32 v69, v237, v69
	v_exp_f32_e32 v243, v75
	v_add_f32_e32 v68, v238, v68
	v_add_f32_e32 v69, v239, v69
	v_exp_f32_e32 v108, v108
	v_exp_f32_e32 v244, v109
	v_exp_f32_e32 v109, v76
	v_add_f32_e32 v68, v104, v68
	v_add_f32_e32 v69, v105, v69
	v_exp_f32_e32 v245, v77
	v_add_f32_e32 v68, v240, v68
	v_add_f32_e32 v69, v241, v69
	v_exp_f32_e32 v110, v110
	v_exp_f32_e32 v246, v111
	v_exp_f32_e32 v111, v78
	v_add_f32_e32 v68, v106, v68
	v_add_f32_e32 v69, v107, v69
	v_exp_f32_e32 v247, v79
	v_add_f32_e32 v68, v242, v68
	v_add_f32_e32 v69, v243, v69
	v_cvt_pk_bf16_f32 v116, v198, v202
	v_cvt_pk_bf16_f32 v117, v204, v206
	v_cvt_pk_bf16_f32 v118, v208, v210
	v_cvt_pk_bf16_f32 v119, v212, v214
	v_cvt_pk_bf16_f32 v112, v120, v216
	s_nop 0
	v_add_f32_e32 v68, v108, v68
	v_add_f32_e32 v69, v109, v69
	v_cvt_pk_bf16_f32 v113, v122, v218
	v_cvt_pk_bf16_f32 v114, v124, v220
	v_cvt_pk_bf16_f32 v115, v126, v222
	v_cvt_pk_bf16_f32 v100, v224, v226
	v_cvt_pk_bf16_f32 v101, v228, v230
	s_nop 0
	v_add_f32_e32 v68, v244, v68
	v_add_f32_e32 v69, v245, v69
	v_cvt_pk_bf16_f32 v102, v232, v234
	v_cvt_pk_bf16_f32 v103, v236, v238
	v_cvt_pk_bf16_f32 v96, v104, v240
	v_cvt_pk_bf16_f32 v97, v106, v242
	v_cvt_pk_bf16_f32 v98, v108, v244
	s_nop 0
	v_add_f32_e32 v68, v110, v68
	v_add_f32_e32 v69, v111, v69
	v_cvt_pk_bf16_f32 v99, v110, v246
	v_cvt_pk_bf16_f32 v80, v199, v203
	v_cvt_pk_bf16_f32 v81, v205, v207
	v_cvt_pk_bf16_f32 v82, v209, v211
	v_cvt_pk_bf16_f32 v83, v213, v215
	s_nop 0
	v_add_f32_e32 v72, v246, v68
	v_add_f32_e32 v73, v247, v69
	v_cvt_pk_bf16_f32 v84, v121, v217
	v_cvt_pk_bf16_f32 v85, v123, v219
	v_cvt_pk_bf16_f32 v86, v125, v221
	v_cvt_pk_bf16_f32 v87, v127, v223
	v_cvt_pk_bf16_f32 v64, v225, v227
	s_nop 0
	v_add_f32_e32 v190, v190, v72
	v_add_f32_e32 v191, v191, v73
	v_cvt_pk_bf16_f32 v65, v229, v231
	v_cvt_pk_bf16_f32 v66, v233, v235
	v_cvt_pk_bf16_f32 v67, v237, v239
	v_cvt_pk_bf16_f32 v68, v105, v241
	v_cvt_pk_bf16_f32 v69, v107, v243
	v_cvt_pk_bf16_f32 v70, v109, v245
	v_cvt_pk_bf16_f32 v71, v111, v247
	ds_read_b64_tr_b16 v[72:73], v195 offset:9216
	ds_read_b64_tr_b16 v[74:75], v195 offset:10368
	s_waitcnt lgkmcnt(0)
	v_mfma_f32_32x32x16_bf16 v[48:63], v[72:75], v[116:119], v[48:63]
	v_mfma_f32_32x32x16_bf16 v[16:31], v[72:75], v[80:83], v[16:31]
	ds_read_b64_tr_b16 v[72:73], v195 offset:9280
	ds_read_b64_tr_b16 v[74:75], v195 offset:10432
	s_waitcnt lgkmcnt(0)
	v_mfma_f32_32x32x16_bf16 v[32:47], v[72:75], v[116:119], v[32:47]
	v_mfma_f32_32x32x16_bf16 v[0:15], v[72:75], v[80:83], v[0:15]
	ds_read_b64_tr_b16 v[72:73], v195 offset:11520
	ds_read_b64_tr_b16 v[74:75], v195 offset:12672
	s_waitcnt lgkmcnt(0)
	v_mfma_f32_32x32x16_bf16 v[48:63], v[72:75], v[112:115], v[48:63]
	v_mfma_f32_32x32x16_bf16 v[16:31], v[72:75], v[84:87], v[16:31]
	ds_read_b64_tr_b16 v[72:73], v195 offset:11584
	ds_read_b64_tr_b16 v[74:75], v195 offset:12736
	s_waitcnt lgkmcnt(0)
	v_mfma_f32_32x32x16_bf16 v[32:47], v[72:75], v[112:115], v[32:47]
	v_mfma_f32_32x32x16_bf16 v[0:15], v[72:75], v[84:87], v[0:15]
	ds_read_b64_tr_b16 v[72:73], v195 offset:13824
	ds_read_b64_tr_b16 v[74:75], v195 offset:14976
	s_waitcnt lgkmcnt(0)
	v_mfma_f32_32x32x16_bf16 v[48:63], v[72:75], v[100:103], v[48:63]
	v_mfma_f32_32x32x16_bf16 v[16:31], v[72:75], v[64:67], v[16:31]
	ds_read_b64_tr_b16 v[72:73], v195 offset:13888
	ds_read_b64_tr_b16 v[74:75], v195 offset:15040
	s_waitcnt lgkmcnt(0)
	v_mfma_f32_32x32x16_bf16 v[0:15], v[72:75], v[64:67], v[0:15]
	ds_read_b64_tr_b16 v[64:65], v195 offset:16128
	ds_read_b64_tr_b16 v[66:67], v195 offset:17280
	v_mfma_f32_32x32x16_bf16 v[32:47], v[72:75], v[100:103], v[32:47]
	s_waitcnt lgkmcnt(0)
	v_mfma_f32_32x32x16_bf16 v[48:63], v[64:67], v[96:99], v[48:63]
	v_mfma_f32_32x32x16_bf16 v[16:31], v[64:67], v[68:71], v[16:31]
	ds_read_b64_tr_b16 v[64:65], v195 offset:16192
	ds_read_b64_tr_b16 v[66:67], v195 offset:17344
	s_waitcnt lgkmcnt(0)
	v_mfma_f32_32x32x16_bf16 v[32:47], v[64:67], v[96:99], v[32:47]
	v_mfma_f32_32x32x16_bf16 v[0:15], v[64:67], v[68:71], v[0:15]
